# P1 forget-gate GEMV: inner loop replaced by straight-line code with 28 loads in flight (was 8, two dependent batches per iteration)
# baseline (speedup 1.0000x reference)
; template <int li> __device__ __forceinline__ void layer_fwd(const Args& args, LAS unsigned char* lds, const int wid_s) {
;     ...
;                 for (int task = gw; task < M / 16; task += NGW) {
;                     const int row0 = task * 16; f32x4 acc = {0.f, 0.f, 0.f, 0.f};
;                     const bf16* ap = HCUR + (size_t)(row0 + fr) * D + 8 * fq; const bf16* bp = Wl + WO_F + fr * 1024 + 8 * fq;
; #pragma unroll 8
;                     for (int kk = 0; kk < 32; ++kk) { const bf16x8 xw = *(const bf16x8*)(bp + 32 * kk), ya = *(const bf16x8*)(ap + 32 * kk);
;                         acc = pg8::mma16<true>(xw, ya, acc); }
.LBB0_307:
	s_waitcnt vmcnt(0)
	global_load_dwordx4 v[64:67], v[14:15], off offset:-256
	global_load_dwordx4 v[68:71], v[16:17], off offset:-256
	global_load_dwordx4 v[72:75], v[14:15], off offset:-192
	global_load_dwordx4 v[76:79], v[16:17], off offset:-192
	global_load_dwordx4 v[80:83], v[14:15], off offset:-128
	global_load_dwordx4 v[84:87], v[16:17], off offset:-128
	global_load_dwordx4 v[88:91], v[14:15], off offset:-64
	global_load_dwordx4 v[92:95], v[16:17], off offset:-64
	global_load_dwordx4 v[96:99], v[14:15], off
	global_load_dwordx4 v[100:103], v[16:17], off
	global_load_dwordx4 v[104:107], v[14:15], off offset:64
	global_load_dwordx4 v[108:111], v[16:17], off offset:64
	global_load_dwordx4 v[112:115], v[14:15], off offset:128
	global_load_dwordx4 v[116:119], v[16:17], off offset:128
	global_load_dwordx4 v[120:123], v[14:15], off offset:192
	global_load_dwordx4 v[124:127], v[16:17], off offset:192
	global_load_dwordx4 v[128:131], v[14:15], off offset:256
	global_load_dwordx4 v[132:135], v[16:17], off offset:256
	global_load_dwordx4 v[136:139], v[14:15], off offset:320
	global_load_dwordx4 v[140:143], v[16:17], off offset:320
	global_load_dwordx4 v[144:147], v[14:15], off offset:384
	global_load_dwordx4 v[148:151], v[16:17], off offset:384
	global_load_dwordx4 v[152:155], v[14:15], off offset:448
	global_load_dwordx4 v[156:159], v[16:17], off offset:448
	global_load_dwordx4 v[160:163], v[14:15], off offset:512
	global_load_dwordx4 v[164:167], v[16:17], off offset:512
	global_load_dwordx4 v[168:171], v[14:15], off offset:576
	global_load_dwordx4 v[172:175], v[16:17], off offset:576
	s_waitcnt vmcnt(26)
	v_mfma_f32_16x16x32_f16 v[0:3], v[64:67], v[68:71], v[0:3]
	global_load_dwordx4 v[64:67], v[14:15], off offset:640
	global_load_dwordx4 v[68:71], v[16:17], off offset:640
	s_waitcnt vmcnt(26)
	v_mfma_f32_16x16x32_f16 v[0:3], v[72:75], v[76:79], v[0:3]
	global_load_dwordx4 v[72:75], v[14:15], off offset:704
	global_load_dwordx4 v[76:79], v[16:17], off offset:704
	s_waitcnt vmcnt(26)
	v_mfma_f32_16x16x32_f16 v[0:3], v[80:83], v[84:87], v[0:3]
	global_load_dwordx4 v[80:83], v[14:15], off offset:768
	global_load_dwordx4 v[84:87], v[16:17], off offset:768
	s_waitcnt vmcnt(26)
	v_mfma_f32_16x16x32_f16 v[0:3], v[88:91], v[92:95], v[0:3]
	global_load_dwordx4 v[88:91], v[14:15], off offset:832
	global_load_dwordx4 v[92:95], v[16:17], off offset:832
	s_waitcnt vmcnt(26)
	v_mfma_f32_16x16x32_f16 v[0:3], v[96:99], v[100:103], v[0:3]
	global_load_dwordx4 v[96:99], v[14:15], off offset:896
	global_load_dwordx4 v[100:103], v[16:17], off offset:896
	s_waitcnt vmcnt(26)
	v_mfma_f32_16x16x32_f16 v[0:3], v[104:107], v[108:111], v[0:3]
	global_load_dwordx4 v[104:107], v[14:15], off offset:960
	global_load_dwordx4 v[108:111], v[16:17], off offset:960
	s_waitcnt vmcnt(26)
	v_mfma_f32_16x16x32_f16 v[0:3], v[112:115], v[116:119], v[0:3]
	global_load_dwordx4 v[112:115], v[14:15], off offset:1024
	global_load_dwordx4 v[116:119], v[16:17], off offset:1024
	s_waitcnt vmcnt(26)
	v_mfma_f32_16x16x32_f16 v[0:3], v[120:123], v[124:127], v[0:3]
	global_load_dwordx4 v[120:123], v[14:15], off offset:1088
	global_load_dwordx4 v[124:127], v[16:17], off offset:1088
	s_waitcnt vmcnt(26)
	v_mfma_f32_16x16x32_f16 v[0:3], v[128:131], v[132:135], v[0:3]
	global_load_dwordx4 v[128:131], v[14:15], off offset:1152
	global_load_dwordx4 v[132:135], v[16:17], off offset:1152
	s_waitcnt vmcnt(26)
	v_mfma_f32_16x16x32_f16 v[0:3], v[136:139], v[140:143], v[0:3]
	global_load_dwordx4 v[136:139], v[14:15], off offset:1216
	global_load_dwordx4 v[140:143], v[16:17], off offset:1216
	s_waitcnt vmcnt(26)
	v_mfma_f32_16x16x32_f16 v[0:3], v[144:147], v[148:151], v[0:3]
	global_load_dwordx4 v[144:147], v[14:15], off offset:1280
	global_load_dwordx4 v[148:151], v[16:17], off offset:1280
	s_waitcnt vmcnt(26)
	v_mfma_f32_16x16x32_f16 v[0:3], v[152:155], v[156:159], v[0:3]
	global_load_dwordx4 v[152:155], v[14:15], off offset:1344
	global_load_dwordx4 v[156:159], v[16:17], off offset:1344
	s_waitcnt vmcnt(26)
	v_mfma_f32_16x16x32_f16 v[0:3], v[160:163], v[164:167], v[0:3]
	global_load_dwordx4 v[160:163], v[14:15], off offset:1408
	global_load_dwordx4 v[164:167], v[16:17], off offset:1408
	s_waitcnt vmcnt(26)
	v_mfma_f32_16x16x32_f16 v[0:3], v[168:171], v[172:175], v[0:3]
	global_load_dwordx4 v[168:171], v[14:15], off offset:1472
	global_load_dwordx4 v[172:175], v[16:17], off offset:1472
	s_waitcnt vmcnt(26)
	v_mfma_f32_16x16x32_f16 v[0:3], v[64:67], v[68:71], v[0:3]
	global_load_dwordx4 v[64:67], v[14:15], off offset:1536
	global_load_dwordx4 v[68:71], v[16:17], off offset:1536
	s_waitcnt vmcnt(26)
	v_mfma_f32_16x16x32_f16 v[0:3], v[72:75], v[76:79], v[0:3]
	global_load_dwordx4 v[72:75], v[14:15], off offset:1600
	global_load_dwordx4 v[76:79], v[16:17], off offset:1600
	s_waitcnt vmcnt(26)
	v_mfma_f32_16x16x32_f16 v[0:3], v[80:83], v[84:87], v[0:3]
	global_load_dwordx4 v[80:83], v[14:15], off offset:1664
	global_load_dwordx4 v[84:87], v[16:17], off offset:1664
	s_waitcnt vmcnt(26)
	v_mfma_f32_16x16x32_f16 v[0:3], v[88:91], v[92:95], v[0:3]
	global_load_dwordx4 v[88:91], v[14:15], off offset:1728
	global_load_dwordx4 v[92:95], v[16:17], off offset:1728
	s_waitcnt vmcnt(26)
	v_mfma_f32_16x16x32_f16 v[0:3], v[96:99], v[100:103], v[0:3]
	s_waitcnt vmcnt(24)
	v_mfma_f32_16x16x32_f16 v[0:3], v[104:107], v[108:111], v[0:3]
	s_waitcnt vmcnt(22)
	v_mfma_f32_16x16x32_f16 v[0:3], v[112:115], v[116:119], v[0:3]
	s_waitcnt vmcnt(20)
	v_mfma_f32_16x16x32_f16 v[0:3], v[120:123], v[124:127], v[0:3]
	s_waitcnt vmcnt(18)
	v_mfma_f32_16x16x32_f16 v[0:3], v[128:131], v[132:135], v[0:3]
	s_waitcnt vmcnt(16)
; __device__ __forceinline__ float rstd_of(float ssq) { return __builtin_amdgcn_rsqf(ssq * (1.0f / 1024.0f) + RMS_EPS); }
; __device__ __forceinline__ float rstd_row(const float* ssq16, int row) { const f32x4* p = (const f32x4*)(ssq16 + (size_t)row * 16); const f32x4 a = p[0], b = p[1], c = p[2], d = p[3];
;     return rstd_of((((a[0] + a[1]) + (a[2] + a[3])) + ((b[0] + b[1]) + (b[2] + b[3]))) + (((c[0] + c[1]) + (c[2] + c[3])) + ((d[0] + d[1]) + (d[2] + d[3])))); }
; template <int li> __device__ __forceinline__ void layer_fwd(const Args& args, LAS unsigned char* lds, const int wid_s) {
;     ...
;                     for (int kk = 0; kk < 32; ++kk) { const bf16x8 xw = *(const bf16x8*)(bp + 32 * kk), ya = *(const bf16x8*)(ap + 32 * kk);
;                         acc = pg8::mma16<true>(xw, ya, acc); }
;                     const int token = row0 + fr; const float rs = pg8::rstd_row(ssq_in, token); const int bb = token >> 12, s = token & 4095;
; #pragma unroll
;                     for (int e = 0; e < 4; ++e) { const int hh = 4 * fq + e; const float f = acc[e] * rs + bfp[hh];
;                         const float lg = fminf(f, 0.f) - log1pf(expf(-fabsf(f))); logf_buf[(size_t)(bb * 16 + hh) * SEQ + s] = lg; }
	v_mfma_f32_16x16x32_f16 v[0:3], v[136:139], v[140:143], v[0:3]
	s_waitcnt vmcnt(14)
	v_mfma_f32_16x16x32_f16 v[0:3], v[144:147], v[148:151], v[0:3]
	s_waitcnt vmcnt(12)
	v_mfma_f32_16x16x32_f16 v[0:3], v[152:155], v[156:159], v[0:3]
	s_waitcnt vmcnt(10)
	v_mfma_f32_16x16x32_f16 v[0:3], v[160:163], v[164:167], v[0:3]
	s_waitcnt vmcnt(8)
	v_mfma_f32_16x16x32_f16 v[0:3], v[168:171], v[172:175], v[0:3]
	s_waitcnt vmcnt(6)
	v_mfma_f32_16x16x32_f16 v[0:3], v[64:67], v[68:71], v[0:3]
	s_waitcnt vmcnt(4)
	v_mfma_f32_16x16x32_f16 v[0:3], v[72:75], v[76:79], v[0:3]
	s_waitcnt vmcnt(2)
	v_mfma_f32_16x16x32_f16 v[0:3], v[80:83], v[84:87], v[0:3]
	s_waitcnt vmcnt(0)
	v_mfma_f32_16x16x32_f16 v[0:3], v[88:91], v[92:95], v[0:3]
	s_lshl_b32 s8, s14, 4
	v_or_b32_e32 v16, s8, v18
	v_ashrrev_i32_e32 v17, 31, v16
	v_lshlrev_b64 v[16:17], 6, v[16:17]
	v_lshl_add_u64 v[16:17], s[10:11], 0, v[16:17]
	global_load_dwordx4 v[26:29], v[16:17], off
	global_load_dwordx4 v[30:33], v[16:17], off offset:32
	global_load_dwordx4 v[34:37], v[16:17], off offset:16
	global_load_dwordx4 v[38:41], v[16:17], off offset:48
	global_load_dword v25, v[6:7], off
	v_bitop3_b32 v11, s8, v22, v18 bitop3:0xc8
	v_lshlrev_b32_e32 v12, 2, v11
	s_ashr_i32 s9, s14, 4
	s_and_b32 s8, s9, -16
	s_add_i32 s14, s14, s33
	s_cmpk_gt_i32 s14, 0x3ff
	v_add_u32_e32 v10, s12, v10
	s_waitcnt vmcnt(4)
	v_mov_b32_e32 v16, v26
	s_waitcnt vmcnt(3)
	v_mov_b32_e32 v17, v30
	v_mov_b32_e32 v30, v27
	v_mov_b32_e32 v26, v28
	v_mov_b32_e32 v27, v32
	v_mov_b32_e32 v32, v29
	s_waitcnt vmcnt(2)
	v_mov_b32_e32 v28, v34
	s_waitcnt vmcnt(1)
	v_mov_b32_e32 v29, v38
	v_mov_b32_e32 v38, v35
	v_mov_b32_e32 v34, v36
	v_mov_b32_e32 v35, v40
	v_mov_b32_e32 v40, v37
	v_pk_add_f32 v[16:17], v[16:17], v[30:31]
	v_pk_add_f32 v[26:27], v[26:27], v[32:33]
	v_pk_add_f32 v[28:29], v[28:29], v[38:39]
	v_pk_add_f32 v[30:31], v[34:35], v[40:41]
	v_pk_add_f32 v[16:17], v[16:17], v[26:27]
	v_pk_add_f32 v[26:27], v[28:29], v[30:31]
	s_nop 0
	v_pk_add_f32 v[16:17], v[16:17], v[26:27]
	v_add_u32_e32 v26, s8, v4
	v_add_f32_e32 v11, v16, v17
	v_fmamk_f32 v11, v11, 0x3a800000, v21
	v_rsq_f32_e32 v11, v11
	v_lshl_add_u64 v[16:17], s[6:7], 0, v[12:13]
	v_ashrrev_i32_e32 v27, 31, v26
	v_lshlrev_b64 v[26:27], 14, v[26:27]
	s_waitcnt vmcnt(0)
	v_fmac_f32_e32 v25, v0, v11
	v_mul_f32_e64 v0, |v25|, s13
	v_fma_f32 v12, |v25|, s13, -v0
	v_rndne_f32_e32 v28, v0
	v_fma_f32 v12, |v25|, s15, v12
	v_sub_f32_e32 v0, v0, v28
	v_add_f32_e32 v0, v0, v12
	v_cvt_i32_f32_e32 v28, v28
	v_exp_f32_e32 v0, v0
	v_cmp_ngt_f32_e64 vcc, |v25|, s16
	v_min_f32_e32 v12, 0, v25
	v_lshl_add_u64 v[26:27], v[16:17], 0, v[26:27]
	v_ldexp_f32 v0, v0, v28
	v_cndmask_b32_e32 v0, 0, v0, vcc
	v_cmp_nlt_f32_e64 vcc, |v25|, s17
	s_nop 1
	v_cndmask_b32_e32 v0, v23, v0, vcc
	v_add_f32_e32 v25, 1.0, v0
	v_add_f32_e32 v30, -1.0, v25
	v_frexp_mant_f32_e32 v31, v25
	v_cvt_f64_f32_e32 v[28:29], v25
	v_sub_f32_e32 v32, v30, v25
	v_frexp_exp_i32_f64_e32 v28, v[28:29]
	v_cmp_gt_f32_e32 vcc, s19, v31
	v_sub_f32_e32 v30, v0, v30
	v_add_f32_e32 v29, 1.0, v32
	v_subbrev_co_u32_e32 v28, vcc, 0, v28, vcc
	v_add_f32_e32 v29, v30, v29
	v_sub_u32_e32 v30, 0, v28
	v_cvt_f32_i32_e32 v28, v28
	v_ldexp_f32 v25, v25, v30
	v_ldexp_f32 v29, v29, v30
	v_add_f32_e32 v30, -1.0, v25
	v_add_f32_e32 v31, 1.0, v25
	v_add_f32_e32 v32, 1.0, v30
	v_add_f32_e32 v33, -1.0, v31
	v_sub_f32_e32 v32, v25, v32
	v_sub_f32_e32 v25, v25, v33
	v_mul_f32_e32 v33, 0x3f317218, v28
	v_add_f32_e32 v32, v29, v32
	v_add_f32_e32 v25, v29, v25
	v_fma_f32 v29, v28, s20, -v33
	v_add_f32_e32 v34, v30, v32
	v_add_f32_e32 v35, v31, v25
	v_fmac_f32_e32 v29, 0xb102e308, v28
	v_sub_f32_e32 v28, v30, v34
	v_sub_f32_e32 v30, v31, v35
	v_rcp_f32_e32 v31, v35
	v_add_f32_e32 v36, v33, v29
	v_add_f32_e32 v25, v25, v30
	v_sub_f32_e32 v30, v36, v33
	v_sub_f32_e32 v29, v29, v30
	v_mul_f32_e32 v30, v34, v31
	v_add_f32_e32 v28, v32, v28
	v_mul_f32_e32 v32, v35, v30
	v_fma_f32 v33, v30, v35, -v32
	v_fmac_f32_e32 v33, v30, v25
	v_add_f32_e32 v37, v32, v33
	v_sub_f32_e32 v38, v34, v37
	v_sub_f32_e32 v32, v37, v32
	v_sub_f32_e32 v34, v34, v38
	v_sub_f32_e32 v32, v32, v33
	v_sub_f32_e32 v33, v34, v37
	v_add_f32_e32 v28, v28, v33
	v_add_f32_e32 v28, v32, v28
	v_add_f32_e32 v32, v38, v28
	v_mul_f32_e32 v33, v31, v32
	v_sub_f32_e32 v34, v38, v32
	v_mul_f32_e32 v37, v35, v33
	v_add_f32_e32 v28, v28, v34
	v_add_f32_e32 v34, v30, v33
	v_fma_f32 v35, v33, v35, -v37
	v_sub_f32_e32 v30, v34, v30
	v_fmac_f32_e32 v35, v33, v25
	v_sub_f32_e32 v25, v33, v30
	v_add_f32_e32 v30, v37, v35
	v_sub_f32_e32 v33, v30, v37
	v_sub_f32_e32 v37, v32, v30
	v_sub_f32_e32 v32, v32, v37
	v_sub_f32_e32 v30, v32, v30
	v_sub_f32_e32 v33, v33, v35
	v_add_f32_e32 v28, v28, v30
	v_add_f32_e32 v28, v33, v28
	v_add_f32_e32 v28, v37, v28
	v_mul_f32_e32 v28, v31, v28
	v_add_f32_e32 v25, v25, v28
	v_add_f32_e32 v28, v34, v25
	v_mul_f32_e32 v30, v28, v28
	v_fmamk_f32 v33, v30, 0x3e9b6dac, v24
	v_sub_f32_e32 v31, v28, v34
	v_ldexp_f32 v32, v28, 1
	v_mul_f32_e32 v28, v28, v30
	v_fmaak_f32 v30, v30, v33, 0x3f2aaada
	v_mul_f32_e32 v28, v28, v30
	v_add_f32_e32 v30, v32, v28
	v_sub_f32_e32 v25, v25, v31
	v_sub_f32_e32 v31, v30, v32
	v_ldexp_f32 v25, v25, 1
	v_sub_f32_e32 v28, v28, v31
	v_add_f32_e32 v25, v25, v28
	v_add_f32_e32 v28, v30, v25
	v_sub_f32_e32 v30, v28, v30
	v_add_f32_e32 v31, v36, v28
	v_sub_f32_e32 v25, v25, v30
	v_sub_f32_e32 v30, v31, v36
	v_sub_f32_e32 v32, v31, v30
	v_sub_f32_e32 v28, v28, v30
	v_add_f32_e32 v30, v29, v25
	v_sub_f32_e32 v32, v36, v32
	v_sub_f32_e32 v33, v30, v29
	v_add_f32_e32 v28, v28, v32
	v_sub_f32_e32 v32, v30, v33
	v_sub_f32_e32 v25, v25, v33
	v_sub_f32_e32 v29, v29, v32
	v_add_f32_e32 v28, v30, v28
	v_add_f32_e32 v25, v25, v29
	v_add_f32_e32 v29, v31, v28
	v_sub_f32_e32 v30, v29, v31
	v_sub_f32_e32 v28, v28, v30
	v_add_f32_e32 v25, v25, v28
	v_add_f32_e32 v25, v29, v25
	v_cmp_neq_f32_e32 vcc, s18, v0
	s_nop 1
	v_cndmask_b32_e32 v25, v23, v25, vcc
	v_cmp_lt_f32_e64 vcc, |v0|, s21
	s_nop 1
	v_cndmask_b32_e32 v0, v25, v0, vcc
	v_sub_f32_e32 v0, v12, v0
	global_store_dword v[26:27], v0, off
	global_load_dword v12, v[6:7], off offset:4
	v_add_u32_e32 v26, s8, v5
	v_ashrrev_i32_e32 v27, 31, v26
	s_waitcnt vmcnt(0)
; template <int li> __device__ __forceinline__ void layer_fwd(const Args& args, LAS unsigned char* lds, const int wid_s) {
;     ...
;                     for (int e = 0; e < 4; ++e) { const int hh = 4 * fq + e; const float f = acc[e] * rs + bfp[hh];
;                         const float lg = fminf(f, 0.f) - log1pf(expf(-fabsf(f))); logf_buf[(size_t)(bb * 16 + hh) * SEQ + s] = lg; }
	v_fmac_f32_e32 v12, v1, v11
	v_mul_f32_e64 v0, |v12|, s13
	v_fma_f32 v1, |v12|, s13, -v0
	v_rndne_f32_e32 v25, v0
	v_fma_f32 v1, |v12|, s15, v1
	v_sub_f32_e32 v0, v0, v25
	v_add_f32_e32 v0, v0, v1
	v_cvt_i32_f32_e32 v25, v25
	v_exp_f32_e32 v28, v0
	v_cmp_ngt_f32_e64 vcc, |v12|, s16
	v_min_f32_e32 v29, 0, v12
	v_lshlrev_b64 v[0:1], 14, v[26:27]
	v_ldexp_f32 v25, v28, v25
	v_cndmask_b32_e32 v25, 0, v25, vcc
	v_cmp_nlt_f32_e64 vcc, |v12|, s17
	v_lshl_add_u64 v[0:1], v[16:17], 0, v[0:1]
	s_nop 0
	v_cndmask_b32_e32 v12, v23, v25, vcc
	v_add_f32_e32 v25, 1.0, v12
	v_add_f32_e32 v28, -1.0, v25
	v_frexp_mant_f32_e32 v30, v25
	v_cvt_f64_f32_e32 v[26:27], v25
	v_sub_f32_e32 v31, v28, v25
	v_frexp_exp_i32_f64_e32 v26, v[26:27]
	v_cmp_gt_f32_e32 vcc, s19, v30
	v_sub_f32_e32 v28, v12, v28
	v_add_f32_e32 v27, 1.0, v31
	v_subbrev_co_u32_e32 v26, vcc, 0, v26, vcc
	v_add_f32_e32 v27, v28, v27
	v_sub_u32_e32 v28, 0, v26
	v_cvt_f32_i32_e32 v26, v26
	v_ldexp_f32 v25, v25, v28
	v_ldexp_f32 v27, v27, v28
	v_add_f32_e32 v28, -1.0, v25
	v_add_f32_e32 v30, 1.0, v25
	v_add_f32_e32 v31, 1.0, v28
	v_add_f32_e32 v32, -1.0, v30
	v_sub_f32_e32 v31, v25, v31
	v_sub_f32_e32 v25, v25, v32
	v_mul_f32_e32 v32, 0x3f317218, v26
	v_add_f32_e32 v31, v27, v31
	v_add_f32_e32 v25, v27, v25
	v_fma_f32 v27, v26, s20, -v32
	v_add_f32_e32 v33, v28, v31
	v_add_f32_e32 v34, v30, v25
	v_fmac_f32_e32 v27, 0xb102e308, v26
	v_sub_f32_e32 v26, v28, v33
	v_sub_f32_e32 v28, v30, v34
	v_rcp_f32_e32 v30, v34
	v_add_f32_e32 v35, v32, v27
	v_add_f32_e32 v25, v25, v28
	v_sub_f32_e32 v28, v35, v32
	v_sub_f32_e32 v27, v27, v28
	v_mul_f32_e32 v28, v33, v30
	v_add_f32_e32 v26, v31, v26
	v_mul_f32_e32 v31, v34, v28
	v_fma_f32 v32, v28, v34, -v31
	v_fmac_f32_e32 v32, v28, v25
	v_add_f32_e32 v36, v31, v32
	v_sub_f32_e32 v37, v33, v36
	v_sub_f32_e32 v31, v36, v31
	v_sub_f32_e32 v33, v33, v37
	v_sub_f32_e32 v31, v31, v32
	v_sub_f32_e32 v32, v33, v36
	v_add_f32_e32 v26, v26, v32
	v_add_f32_e32 v26, v31, v26
	v_add_f32_e32 v31, v37, v26
	v_mul_f32_e32 v32, v30, v31
	v_sub_f32_e32 v33, v37, v31
	v_mul_f32_e32 v36, v34, v32
	v_add_f32_e32 v26, v26, v33
	v_add_f32_e32 v33, v28, v32
	v_fma_f32 v34, v32, v34, -v36
	v_sub_f32_e32 v28, v33, v28
	v_fmac_f32_e32 v34, v32, v25
	v_sub_f32_e32 v25, v32, v28
	v_add_f32_e32 v28, v36, v34
	v_sub_f32_e32 v32, v28, v36
	v_sub_f32_e32 v36, v31, v28
	v_sub_f32_e32 v31, v31, v36
	v_sub_f32_e32 v28, v31, v28
	v_sub_f32_e32 v32, v32, v34
	v_add_f32_e32 v26, v26, v28
	v_add_f32_e32 v26, v32, v26
	v_add_f32_e32 v26, v36, v26
	v_mul_f32_e32 v26, v30, v26
	v_add_f32_e32 v25, v25, v26
	v_add_f32_e32 v26, v33, v25
	v_mul_f32_e32 v28, v26, v26
	v_fmamk_f32 v32, v28, 0x3e9b6dac, v24
	v_sub_f32_e32 v30, v26, v33
	v_ldexp_f32 v31, v26, 1
	v_mul_f32_e32 v26, v26, v28
	v_fmaak_f32 v28, v28, v32, 0x3f2aaada
	v_mul_f32_e32 v26, v26, v28
	v_add_f32_e32 v28, v31, v26
	v_sub_f32_e32 v25, v25, v30
	v_sub_f32_e32 v30, v28, v31
	v_ldexp_f32 v25, v25, 1
	v_sub_f32_e32 v26, v26, v30
	v_add_f32_e32 v25, v25, v26
	v_add_f32_e32 v26, v28, v25
	v_sub_f32_e32 v28, v26, v28
	v_add_f32_e32 v30, v35, v26
	v_sub_f32_e32 v25, v25, v28
	v_sub_f32_e32 v28, v30, v35
	v_sub_f32_e32 v31, v30, v28
	v_sub_f32_e32 v26, v26, v28
	v_add_f32_e32 v28, v27, v25
	v_sub_f32_e32 v31, v35, v31
	v_sub_f32_e32 v32, v28, v27
	v_add_f32_e32 v26, v26, v31
	v_sub_f32_e32 v31, v28, v32
	v_sub_f32_e32 v25, v25, v32
	v_sub_f32_e32 v27, v27, v31
	v_add_f32_e32 v26, v28, v26
	v_add_f32_e32 v25, v25, v27
	v_add_f32_e32 v27, v30, v26
	v_sub_f32_e32 v28, v27, v30
	v_sub_f32_e32 v26, v26, v28
	v_add_f32_e32 v25, v25, v26
	v_add_f32_e32 v25, v27, v25
	v_cmp_neq_f32_e32 vcc, s18, v12
	s_nop 1
	v_cndmask_b32_e32 v25, v23, v25, vcc
	v_cmp_lt_f32_e64 vcc, |v12|, s21
	s_nop 1
	v_cndmask_b32_e32 v12, v25, v12, vcc
	v_sub_f32_e32 v12, v29, v12
	global_store_dword v[0:1], v12, off
	global_load_dword v12, v[6:7], off offset:8
	v_add_u32_e32 v0, s8, v19
	v_ashrrev_i32_e32 v1, 31, v0
	v_lshlrev_b64 v[0:1], 14, v[0:1]
	v_lshl_add_u64 v[0:1], v[16:17], 0, v[0:1]
	s_waitcnt vmcnt(0)
	v_fmac_f32_e32 v12, v2, v11
	v_mul_f32_e64 v2, |v12|, s13
	v_fma_f32 v25, |v12|, s13, -v2
	v_rndne_f32_e32 v26, v2
	v_fma_f32 v25, |v12|, s15, v25
	v_sub_f32_e32 v2, v2, v26
	v_add_f32_e32 v2, v2, v25
	v_cvt_i32_f32_e32 v26, v26
	v_exp_f32_e32 v2, v2
	v_cmp_ngt_f32_e64 vcc, |v12|, s16
	v_min_f32_e32 v25, 0, v12
	v_ldexp_f32 v2, v2, v26
	v_cndmask_b32_e32 v2, 0, v2, vcc
	v_cmp_nlt_f32_e64 vcc, |v12|, s17
	s_nop 1
	v_cndmask_b32_e32 v2, v23, v2, vcc
	v_add_f32_e32 v12, 1.0, v2
	v_add_f32_e32 v28, -1.0, v12
	v_frexp_mant_f32_e32 v29, v12
	v_cvt_f64_f32_e32 v[26:27], v12
	v_sub_f32_e32 v30, v28, v12
	v_frexp_exp_i32_f64_e32 v26, v[26:27]
	v_cmp_gt_f32_e32 vcc, s19, v29
	v_sub_f32_e32 v28, v2, v28
	v_add_f32_e32 v27, 1.0, v30
	v_subbrev_co_u32_e32 v26, vcc, 0, v26, vcc
	v_add_f32_e32 v27, v28, v27
	v_sub_u32_e32 v28, 0, v26
	v_cvt_f32_i32_e32 v26, v26
	v_ldexp_f32 v12, v12, v28
	v_ldexp_f32 v27, v27, v28
	v_add_f32_e32 v28, -1.0, v12
	v_add_f32_e32 v29, 1.0, v12
	v_add_f32_e32 v30, 1.0, v28
	v_add_f32_e32 v31, -1.0, v29
	v_sub_f32_e32 v30, v12, v30
	v_sub_f32_e32 v12, v12, v31
	v_mul_f32_e32 v31, 0x3f317218, v26
	v_add_f32_e32 v30, v27, v30
	v_add_f32_e32 v12, v27, v12
	v_fma_f32 v27, v26, s20, -v31
	v_add_f32_e32 v32, v28, v30
	v_add_f32_e32 v33, v29, v12
	v_fmac_f32_e32 v27, 0xb102e308, v26
	v_sub_f32_e32 v26, v28, v32
	v_sub_f32_e32 v28, v29, v33
	v_rcp_f32_e32 v29, v33
	v_add_f32_e32 v34, v31, v27
	v_add_f32_e32 v12, v12, v28
	v_sub_f32_e32 v28, v34, v31
	v_sub_f32_e32 v27, v27, v28
	v_mul_f32_e32 v28, v32, v29
	v_add_f32_e32 v26, v30, v26
	v_mul_f32_e32 v30, v33, v28
; template <int li> __device__ __forceinline__ void layer_fwd(const Args& args, LAS unsigned char* lds, const int wid_s) {
;     ...
;                 for (int task = gw; task < M / 16; task += NGW) {
;     ...
;                     for (int e = 0; e < 4; ++e) { const int hh = 4 * fq + e; const float f = acc[e] * rs + bfp[hh];
;                         const float lg = fminf(f, 0.f) - log1pf(expf(-fabsf(f))); logf_buf[(size_t)(bb * 16 + hh) * SEQ + s] = lg; }
	v_fma_f32 v31, v28, v33, -v30
	v_fmac_f32_e32 v31, v28, v12
	v_add_f32_e32 v35, v30, v31
	v_sub_f32_e32 v36, v32, v35
	v_sub_f32_e32 v30, v35, v30
	v_sub_f32_e32 v32, v32, v36
	v_sub_f32_e32 v30, v30, v31
	v_sub_f32_e32 v31, v32, v35
	v_add_f32_e32 v26, v26, v31
	v_add_f32_e32 v26, v30, v26
	v_add_f32_e32 v30, v36, v26
	v_mul_f32_e32 v31, v29, v30
	v_sub_f32_e32 v32, v36, v30
	v_mul_f32_e32 v35, v33, v31
	v_add_f32_e32 v26, v26, v32
	v_add_f32_e32 v32, v28, v31
	v_fma_f32 v33, v31, v33, -v35
	v_sub_f32_e32 v28, v32, v28
	v_fmac_f32_e32 v33, v31, v12
	v_sub_f32_e32 v12, v31, v28
	v_add_f32_e32 v28, v35, v33
	v_sub_f32_e32 v31, v28, v35
	v_sub_f32_e32 v35, v30, v28
	v_sub_f32_e32 v30, v30, v35
	v_sub_f32_e32 v28, v30, v28
	v_sub_f32_e32 v31, v31, v33
	v_add_f32_e32 v26, v26, v28
	v_add_f32_e32 v26, v31, v26
	v_add_f32_e32 v26, v35, v26
	v_mul_f32_e32 v26, v29, v26
	v_add_f32_e32 v12, v12, v26
	v_add_f32_e32 v26, v32, v12
	v_mul_f32_e32 v28, v26, v26
	v_fmamk_f32 v31, v28, 0x3e9b6dac, v24
	v_sub_f32_e32 v29, v26, v32
	v_ldexp_f32 v30, v26, 1
	v_mul_f32_e32 v26, v26, v28
	v_fmaak_f32 v28, v28, v31, 0x3f2aaada
	v_mul_f32_e32 v26, v26, v28
	v_add_f32_e32 v28, v30, v26
	v_sub_f32_e32 v12, v12, v29
	v_sub_f32_e32 v29, v28, v30
	v_ldexp_f32 v12, v12, 1
	v_sub_f32_e32 v26, v26, v29
	v_add_f32_e32 v12, v12, v26
	v_add_f32_e32 v26, v28, v12
	v_sub_f32_e32 v28, v26, v28
	v_add_f32_e32 v29, v34, v26
	v_sub_f32_e32 v12, v12, v28
	v_sub_f32_e32 v28, v29, v34
	v_sub_f32_e32 v30, v29, v28
	v_sub_f32_e32 v26, v26, v28
	v_add_f32_e32 v28, v27, v12
	v_sub_f32_e32 v30, v34, v30
	v_sub_f32_e32 v31, v28, v27
	v_add_f32_e32 v26, v26, v30
	v_sub_f32_e32 v30, v28, v31
	v_sub_f32_e32 v12, v12, v31
	v_sub_f32_e32 v27, v27, v30
	v_add_f32_e32 v26, v28, v26
	v_add_f32_e32 v12, v12, v27
	v_add_f32_e32 v27, v29, v26
	v_sub_f32_e32 v28, v27, v29
	v_sub_f32_e32 v26, v26, v28
	v_add_f32_e32 v12, v12, v26
	v_add_f32_e32 v12, v27, v12
	v_cmp_neq_f32_e32 vcc, s18, v2
	s_nop 1
	v_cndmask_b32_e32 v12, v23, v12, vcc
	v_cmp_lt_f32_e64 vcc, |v2|, s21
	s_nop 1
	v_cndmask_b32_e32 v2, v12, v2, vcc
	v_sub_f32_e32 v2, v25, v2
	global_store_dword v[0:1], v2, off
	global_load_dword v2, v[6:7], off offset:12
	v_add_u32_e32 v0, s8, v20
	v_ashrrev_i32_e32 v1, 31, v0
	v_lshlrev_b64 v[0:1], 14, v[0:1]
	v_lshl_add_u64 v[0:1], v[16:17], 0, v[0:1]
	s_waitcnt vmcnt(0)
	v_fmac_f32_e32 v2, v3, v11
	v_mul_f32_e64 v3, |v2|, s13
	v_fma_f32 v11, |v2|, s13, -v3
	v_rndne_f32_e32 v12, v3
	v_fma_f32 v11, |v2|, s15, v11
	v_sub_f32_e32 v3, v3, v12
	v_add_f32_e32 v3, v3, v11
	v_cvt_i32_f32_e32 v12, v12
	v_exp_f32_e32 v3, v3
	v_cmp_ngt_f32_e64 vcc, |v2|, s16
	v_min_f32_e32 v11, 0, v2
	v_ldexp_f32 v3, v3, v12
	v_cndmask_b32_e32 v3, 0, v3, vcc
	v_cmp_nlt_f32_e64 vcc, |v2|, s17
	s_nop 1
	v_cndmask_b32_e32 v12, v23, v3, vcc
	v_add_f32_e32 v16, 1.0, v12
	v_add_f32_e32 v17, -1.0, v16
	v_frexp_mant_f32_e32 v25, v16
	v_cvt_f64_f32_e32 v[2:3], v16
	v_sub_f32_e32 v26, v17, v16
	v_frexp_exp_i32_f64_e32 v2, v[2:3]
	v_cmp_gt_f32_e32 vcc, s19, v25
	v_sub_f32_e32 v17, v12, v17
	v_add_f32_e32 v3, 1.0, v26
	v_subbrev_co_u32_e32 v2, vcc, 0, v2, vcc
	v_add_f32_e32 v3, v17, v3
	v_sub_u32_e32 v17, 0, v2
	v_cvt_f32_i32_e32 v2, v2
	v_ldexp_f32 v16, v16, v17
	v_ldexp_f32 v3, v3, v17
	v_add_f32_e32 v17, -1.0, v16
	v_add_f32_e32 v25, 1.0, v16
	v_add_f32_e32 v26, 1.0, v17
	v_add_f32_e32 v27, -1.0, v25
	v_sub_f32_e32 v26, v16, v26
	v_sub_f32_e32 v16, v16, v27
	v_mul_f32_e32 v27, 0x3f317218, v2
	v_add_f32_e32 v26, v3, v26
	v_add_f32_e32 v3, v3, v16
	v_fma_f32 v16, v2, s20, -v27
	v_add_f32_e32 v28, v17, v26
	v_add_f32_e32 v29, v25, v3
	v_fmac_f32_e32 v16, 0xb102e308, v2
	v_sub_f32_e32 v2, v17, v28
	v_sub_f32_e32 v17, v25, v29
	v_rcp_f32_e32 v25, v29
	v_add_f32_e32 v30, v27, v16
	v_add_f32_e32 v3, v3, v17
	v_sub_f32_e32 v17, v30, v27
	v_sub_f32_e32 v16, v16, v17
	v_mul_f32_e32 v17, v28, v25
	v_add_f32_e32 v2, v26, v2
	v_mul_f32_e32 v26, v29, v17
	v_fma_f32 v27, v17, v29, -v26
	v_fmac_f32_e32 v27, v17, v3
	v_add_f32_e32 v31, v26, v27
	v_sub_f32_e32 v32, v28, v31
	v_sub_f32_e32 v26, v31, v26
	v_sub_f32_e32 v28, v28, v32
	v_sub_f32_e32 v26, v26, v27
	v_sub_f32_e32 v27, v28, v31
	v_add_f32_e32 v2, v2, v27
	v_add_f32_e32 v2, v26, v2
	v_add_f32_e32 v26, v32, v2
	v_mul_f32_e32 v27, v25, v26
	v_sub_f32_e32 v28, v32, v26
	v_mul_f32_e32 v31, v29, v27
	v_add_f32_e32 v2, v2, v28
	v_add_f32_e32 v28, v17, v27
	v_fma_f32 v29, v27, v29, -v31
	v_sub_f32_e32 v17, v28, v17
	v_fmac_f32_e32 v29, v27, v3
	v_sub_f32_e32 v3, v27, v17
	v_add_f32_e32 v17, v31, v29
	v_sub_f32_e32 v27, v17, v31
	v_sub_f32_e32 v31, v26, v17
	v_sub_f32_e32 v26, v26, v31
	v_sub_f32_e32 v17, v26, v17
	v_sub_f32_e32 v27, v27, v29
	v_add_f32_e32 v2, v2, v17
	v_add_f32_e32 v2, v27, v2
	v_add_f32_e32 v2, v31, v2
	v_mul_f32_e32 v2, v25, v2
	v_add_f32_e32 v2, v3, v2
	v_add_f32_e32 v3, v28, v2
	v_mul_f32_e32 v17, v3, v3
	v_fmamk_f32 v27, v17, 0x3e9b6dac, v24
	v_sub_f32_e32 v25, v3, v28
	v_ldexp_f32 v26, v3, 1
	v_mul_f32_e32 v3, v3, v17
	v_fmaak_f32 v17, v17, v27, 0x3f2aaada
	v_mul_f32_e32 v3, v3, v17
	v_add_f32_e32 v17, v26, v3
	v_sub_f32_e32 v2, v2, v25
	v_sub_f32_e32 v25, v17, v26
	v_ldexp_f32 v2, v2, 1
	v_sub_f32_e32 v3, v3, v25
	v_add_f32_e32 v2, v2, v3
	v_add_f32_e32 v3, v17, v2
	v_sub_f32_e32 v17, v3, v17
	v_add_f32_e32 v25, v30, v3
	v_sub_f32_e32 v2, v2, v17
	v_sub_f32_e32 v17, v25, v30
	v_sub_f32_e32 v26, v25, v17
	v_sub_f32_e32 v3, v3, v17
	v_add_f32_e32 v17, v16, v2
	v_sub_f32_e32 v26, v30, v26
	v_sub_f32_e32 v27, v17, v16
	v_add_f32_e32 v3, v3, v26
	v_sub_f32_e32 v26, v17, v27
	v_sub_f32_e32 v2, v2, v27
	v_sub_f32_e32 v16, v16, v26
	v_add_f32_e32 v3, v17, v3
	v_add_f32_e32 v2, v2, v16
	v_add_f32_e32 v16, v25, v3
	v_sub_f32_e32 v17, v16, v25
	v_sub_f32_e32 v3, v3, v17
	v_add_f32_e32 v2, v2, v3
	v_add_f32_e32 v2, v16, v2
	v_cmp_neq_f32_e32 vcc, s18, v12
	s_nop 1
	v_cndmask_b32_e32 v2, v23, v2, vcc
	v_cmp_lt_f32_e64 vcc, |v12|, s21
	s_nop 1
	v_cndmask_b32_e32 v2, v2, v12, vcc
	v_sub_f32_e32 v2, v11, v2
	global_store_dword v[0:1], v2, off
	s_cbranch_scc0 .LBB0_306

; template <int li> __device__ __forceinline__ void layer_fwd(const Args& args, LAS unsigned char* lds, const int wid_s) {
;     ...
;                     const bf16* ap = HCUR + (size_t)(row0 + fr) * D + 8 * fq; const bf16* bp = Wl + WO_F + fr * 1024 + 8 * fq;
; #pragma unroll 8
;                     for (int kk = 0; kk < 32; ++kk) { const bf16x8 xw = *(const bf16x8*)(bp + 32 * kk), ya = *(const bf16x8*)(ap + 32 * kk);
;                         acc = pg8::mma16<true>(xw, ya, acc); }
.LBB0_1631:
	s_waitcnt vmcnt(0)
	global_load_dwordx4 v[64:67], v[14:15], off offset:-256
	global_load_dwordx4 v[68:71], v[16:17], off offset:-256
	global_load_dwordx4 v[72:75], v[14:15], off offset:-192
	global_load_dwordx4 v[76:79], v[16:17], off offset:-192
	global_load_dwordx4 v[80:83], v[14:15], off offset:-128
	global_load_dwordx4 v[84:87], v[16:17], off offset:-128
	global_load_dwordx4 v[88:91], v[14:15], off offset:-64
	global_load_dwordx4 v[92:95], v[16:17], off offset:-64
	global_load_dwordx4 v[96:99], v[14:15], off
	global_load_dwordx4 v[100:103], v[16:17], off
	global_load_dwordx4 v[104:107], v[14:15], off offset:64
	global_load_dwordx4 v[108:111], v[16:17], off offset:64
	global_load_dwordx4 v[112:115], v[14:15], off offset:128
	global_load_dwordx4 v[116:119], v[16:17], off offset:128
	global_load_dwordx4 v[120:123], v[14:15], off offset:192
	global_load_dwordx4 v[124:127], v[16:17], off offset:192
	global_load_dwordx4 v[128:131], v[14:15], off offset:256
	global_load_dwordx4 v[132:135], v[16:17], off offset:256
	global_load_dwordx4 v[136:139], v[14:15], off offset:320
	global_load_dwordx4 v[140:143], v[16:17], off offset:320
	global_load_dwordx4 v[144:147], v[14:15], off offset:384
	global_load_dwordx4 v[148:151], v[16:17], off offset:384
	global_load_dwordx4 v[152:155], v[14:15], off offset:448
	global_load_dwordx4 v[156:159], v[16:17], off offset:448
	global_load_dwordx4 v[160:163], v[14:15], off offset:512
	global_load_dwordx4 v[164:167], v[16:17], off offset:512
	global_load_dwordx4 v[168:171], v[14:15], off offset:576
	global_load_dwordx4 v[172:175], v[16:17], off offset:576
	s_waitcnt vmcnt(26)
	v_mfma_f32_16x16x32_f16 v[0:3], v[64:67], v[68:71], v[0:3]
	global_load_dwordx4 v[64:67], v[14:15], off offset:640
	global_load_dwordx4 v[68:71], v[16:17], off offset:640
	s_waitcnt vmcnt(26)
	v_mfma_f32_16x16x32_f16 v[0:3], v[72:75], v[76:79], v[0:3]
	global_load_dwordx4 v[72:75], v[14:15], off offset:704
	global_load_dwordx4 v[76:79], v[16:17], off offset:704
	s_waitcnt vmcnt(26)
	v_mfma_f32_16x16x32_f16 v[0:3], v[80:83], v[84:87], v[0:3]
	global_load_dwordx4 v[80:83], v[14:15], off offset:768
	global_load_dwordx4 v[84:87], v[16:17], off offset:768
	s_waitcnt vmcnt(26)
	v_mfma_f32_16x16x32_f16 v[0:3], v[88:91], v[92:95], v[0:3]
	global_load_dwordx4 v[88:91], v[14:15], off offset:832
	global_load_dwordx4 v[92:95], v[16:17], off offset:832
	s_waitcnt vmcnt(26)
	v_mfma_f32_16x16x32_f16 v[0:3], v[96:99], v[100:103], v[0:3]
	global_load_dwordx4 v[96:99], v[14:15], off offset:896
	global_load_dwordx4 v[100:103], v[16:17], off offset:896
	s_waitcnt vmcnt(26)
	v_mfma_f32_16x16x32_f16 v[0:3], v[104:107], v[108:111], v[0:3]
	global_load_dwordx4 v[104:107], v[14:15], off offset:960
	global_load_dwordx4 v[108:111], v[16:17], off offset:960
	s_waitcnt vmcnt(26)
	v_mfma_f32_16x16x32_f16 v[0:3], v[112:115], v[116:119], v[0:3]
	global_load_dwordx4 v[112:115], v[14:15], off offset:1024
	global_load_dwordx4 v[116:119], v[16:17], off offset:1024
	s_waitcnt vmcnt(26)
	v_mfma_f32_16x16x32_f16 v[0:3], v[120:123], v[124:127], v[0:3]
	global_load_dwordx4 v[120:123], v[14:15], off offset:1088
	global_load_dwordx4 v[124:127], v[16:17], off offset:1088
	s_waitcnt vmcnt(26)
	v_mfma_f32_16x16x32_f16 v[0:3], v[128:131], v[132:135], v[0:3]
	global_load_dwordx4 v[128:131], v[14:15], off offset:1152
	global_load_dwordx4 v[132:135], v[16:17], off offset:1152
	s_waitcnt vmcnt(26)
	v_mfma_f32_16x16x32_f16 v[0:3], v[136:139], v[140:143], v[0:3]
	global_load_dwordx4 v[136:139], v[14:15], off offset:1216
	global_load_dwordx4 v[140:143], v[16:17], off offset:1216
	s_waitcnt vmcnt(26)
	v_mfma_f32_16x16x32_f16 v[0:3], v[144:147], v[148:151], v[0:3]
	global_load_dwordx4 v[144:147], v[14:15], off offset:1280
	global_load_dwordx4 v[148:151], v[16:17], off offset:1280
	s_waitcnt vmcnt(26)
	v_mfma_f32_16x16x32_f16 v[0:3], v[152:155], v[156:159], v[0:3]
	global_load_dwordx4 v[152:155], v[14:15], off offset:1344
	global_load_dwordx4 v[156:159], v[16:17], off offset:1344
	s_waitcnt vmcnt(26)
	v_mfma_f32_16x16x32_f16 v[0:3], v[160:163], v[164:167], v[0:3]
	global_load_dwordx4 v[160:163], v[14:15], off offset:1408
	global_load_dwordx4 v[164:167], v[16:17], off offset:1408
	s_waitcnt vmcnt(26)
	v_mfma_f32_16x16x32_f16 v[0:3], v[168:171], v[172:175], v[0:3]
	global_load_dwordx4 v[168:171], v[14:15], off offset:1472
	global_load_dwordx4 v[172:175], v[16:17], off offset:1472
	s_waitcnt vmcnt(26)
	v_mfma_f32_16x16x32_f16 v[0:3], v[64:67], v[68:71], v[0:3]
	global_load_dwordx4 v[64:67], v[14:15], off offset:1536
	global_load_dwordx4 v[68:71], v[16:17], off offset:1536
	s_waitcnt vmcnt(26)
	v_mfma_f32_16x16x32_f16 v[0:3], v[72:75], v[76:79], v[0:3]
	global_load_dwordx4 v[72:75], v[14:15], off offset:1600
	global_load_dwordx4 v[76:79], v[16:17], off offset:1600
	s_waitcnt vmcnt(26)
	v_mfma_f32_16x16x32_f16 v[0:3], v[80:83], v[84:87], v[0:3]
	global_load_dwordx4 v[80:83], v[14:15], off offset:1664
	global_load_dwordx4 v[84:87], v[16:17], off offset:1664
	s_waitcnt vmcnt(26)
	v_mfma_f32_16x16x32_f16 v[0:3], v[88:91], v[92:95], v[0:3]
	global_load_dwordx4 v[88:91], v[14:15], off offset:1728
	global_load_dwordx4 v[92:95], v[16:17], off offset:1728
	s_waitcnt vmcnt(26)
	v_mfma_f32_16x16x32_f16 v[0:3], v[96:99], v[100:103], v[0:3]
	s_waitcnt vmcnt(24)
	v_mfma_f32_16x16x32_f16 v[0:3], v[104:107], v[108:111], v[0:3]
	s_waitcnt vmcnt(22)
	v_mfma_f32_16x16x32_f16 v[0:3], v[112:115], v[116:119], v[0:3]
	s_waitcnt vmcnt(20)
	v_mfma_f32_16x16x32_f16 v[0:3], v[120:123], v[124:127], v[0:3]
	s_waitcnt vmcnt(18)
	v_mfma_f32_16x16x32_f16 v[0:3], v[128:131], v[132:135], v[0:3]
	s_waitcnt vmcnt(16)
; __device__ __forceinline__ float rstd_of(float ssq) { return __builtin_amdgcn_rsqf(ssq * (1.0f / 1024.0f) + RMS_EPS); }
; __device__ __forceinline__ float rstd_row(const float* ssq16, int row) { const f32x4* p = (const f32x4*)(ssq16 + (size_t)row * 16); const f32x4 a = p[0], b = p[1], c = p[2], d = p[3];
;     return rstd_of((((a[0] + a[1]) + (a[2] + a[3])) + ((b[0] + b[1]) + (b[2] + b[3]))) + (((c[0] + c[1]) + (c[2] + c[3])) + ((d[0] + d[1]) + (d[2] + d[3])))); }
; template <int li> __device__ __forceinline__ void layer_fwd(const Args& args, LAS unsigned char* lds, const int wid_s) {
;     ...
;                     for (int kk = 0; kk < 32; ++kk) { const bf16x8 xw = *(const bf16x8*)(bp + 32 * kk), ya = *(const bf16x8*)(ap + 32 * kk);
;                         acc = pg8::mma16<true>(xw, ya, acc); }
;                     const int token = row0 + fr; const float rs = pg8::rstd_row(ssq_in, token); const int bb = token >> 12, s = token & 4095;
; #pragma unroll
;                     for (int e = 0; e < 4; ++e) { const int hh = 4 * fq + e; const float f = acc[e] * rs + bfp[hh];
;                         const float lg = fminf(f, 0.f) - log1pf(expf(-fabsf(f))); logf_buf[(size_t)(bb * 16 + hh) * SEQ + s] = lg; }
	v_mfma_f32_16x16x32_f16 v[0:3], v[136:139], v[140:143], v[0:3]
	s_waitcnt vmcnt(14)
	v_mfma_f32_16x16x32_f16 v[0:3], v[144:147], v[148:151], v[0:3]
	s_waitcnt vmcnt(12)
	v_mfma_f32_16x16x32_f16 v[0:3], v[152:155], v[156:159], v[0:3]
	s_waitcnt vmcnt(10)
	v_mfma_f32_16x16x32_f16 v[0:3], v[160:163], v[164:167], v[0:3]
	s_waitcnt vmcnt(8)
	v_mfma_f32_16x16x32_f16 v[0:3], v[168:171], v[172:175], v[0:3]
	s_waitcnt vmcnt(6)
	v_mfma_f32_16x16x32_f16 v[0:3], v[64:67], v[68:71], v[0:3]
	s_waitcnt vmcnt(4)
	v_mfma_f32_16x16x32_f16 v[0:3], v[72:75], v[76:79], v[0:3]
	s_waitcnt vmcnt(2)
	v_mfma_f32_16x16x32_f16 v[0:3], v[80:83], v[84:87], v[0:3]
	s_waitcnt vmcnt(0)
	v_mfma_f32_16x16x32_f16 v[0:3], v[88:91], v[92:95], v[0:3]
	s_lshl_b32 s12, s14, 4
	v_or_b32_e32 v16, s12, v18
	v_ashrrev_i32_e32 v17, 31, v16
	v_lshlrev_b64 v[16:17], 6, v[16:17]
	v_lshl_add_u64 v[16:17], s[22:23], 0, v[16:17]
	global_load_dwordx4 v[26:29], v[16:17], off
	global_load_dwordx4 v[30:33], v[16:17], off offset:32
	global_load_dwordx4 v[34:37], v[16:17], off offset:16
	global_load_dwordx4 v[38:41], v[16:17], off offset:48
	global_load_dword v25, v[6:7], off offset:64
	v_bitop3_b32 v11, s12, v22, v18 bitop3:0xc8
	v_lshlrev_b32_e32 v12, 2, v11
	s_ashr_i32 s13, s14, 4
	s_and_b32 s12, s13, -16
	s_add_i32 s14, s14, s33
	s_cmpk_gt_i32 s14, 0x3ff
	v_add_u32_e32 v10, s15, v10
	s_waitcnt vmcnt(4)
	v_mov_b32_e32 v16, v26
	s_waitcnt vmcnt(3)
	v_mov_b32_e32 v17, v30
	v_mov_b32_e32 v30, v27
	v_mov_b32_e32 v26, v28
	v_mov_b32_e32 v27, v32
	v_mov_b32_e32 v32, v29
	s_waitcnt vmcnt(2)
	v_mov_b32_e32 v28, v34
	s_waitcnt vmcnt(1)
	v_mov_b32_e32 v29, v38
	v_mov_b32_e32 v38, v35
	v_mov_b32_e32 v34, v36
	v_mov_b32_e32 v35, v40
	v_mov_b32_e32 v40, v37
	v_pk_add_f32 v[16:17], v[16:17], v[30:31]
	v_pk_add_f32 v[26:27], v[26:27], v[32:33]
	v_pk_add_f32 v[28:29], v[28:29], v[38:39]
	v_pk_add_f32 v[30:31], v[34:35], v[40:41]
	v_pk_add_f32 v[16:17], v[16:17], v[26:27]
	v_pk_add_f32 v[26:27], v[28:29], v[30:31]
	s_nop 0
	v_pk_add_f32 v[16:17], v[16:17], v[26:27]
	v_add_u32_e32 v26, s12, v4
	v_add_f32_e32 v11, v16, v17
	v_fmamk_f32 v11, v11, 0x3a800000, v21
	v_rsq_f32_e32 v11, v11
	v_lshl_add_u64 v[16:17], s[10:11], 0, v[12:13]
	v_ashrrev_i32_e32 v27, 31, v26
	v_lshlrev_b64 v[26:27], 14, v[26:27]
	s_waitcnt vmcnt(0)
	v_fmac_f32_e32 v25, v0, v11
	v_mul_f32_e64 v0, |v25|, s19
	v_fma_f32 v12, |v25|, s19, -v0
	v_rndne_f32_e32 v28, v0
	v_fma_f32 v12, |v25|, s21, v12
	v_sub_f32_e32 v0, v0, v28
	v_add_f32_e32 v0, v0, v12
	v_cvt_i32_f32_e32 v28, v28
	v_exp_f32_e32 v0, v0
	v_cmp_ngt_f32_e64 vcc, |v25|, s24
	v_min_f32_e32 v12, 0, v25
	v_lshl_add_u64 v[26:27], v[16:17], 0, v[26:27]
	v_ldexp_f32 v0, v0, v28
	v_cndmask_b32_e32 v0, 0, v0, vcc
	v_cmp_nlt_f32_e64 vcc, |v25|, s25
	s_nop 1
	v_cndmask_b32_e32 v0, v23, v0, vcc
	v_add_f32_e32 v25, 1.0, v0
	v_add_f32_e32 v30, -1.0, v25
	v_frexp_mant_f32_e32 v31, v25
	v_cvt_f64_f32_e32 v[28:29], v25
	v_sub_f32_e32 v32, v30, v25
	v_frexp_exp_i32_f64_e32 v28, v[28:29]
	v_cmp_gt_f32_e32 vcc, s27, v31
	v_sub_f32_e32 v30, v0, v30
	v_add_f32_e32 v29, 1.0, v32
	v_subbrev_co_u32_e32 v28, vcc, 0, v28, vcc
	v_add_f32_e32 v29, v30, v29
	v_sub_u32_e32 v30, 0, v28
	v_cvt_f32_i32_e32 v28, v28
	v_ldexp_f32 v25, v25, v30
	v_ldexp_f32 v29, v29, v30
	v_add_f32_e32 v30, -1.0, v25
	v_add_f32_e32 v31, 1.0, v25
	v_add_f32_e32 v32, 1.0, v30
	v_add_f32_e32 v33, -1.0, v31
	v_sub_f32_e32 v32, v25, v32
	v_sub_f32_e32 v25, v25, v33
	v_mul_f32_e32 v33, 0x3f317218, v28
	v_add_f32_e32 v32, v29, v32
	v_add_f32_e32 v25, v29, v25
	v_fma_f32 v29, v28, s28, -v33
	v_add_f32_e32 v34, v30, v32
	v_add_f32_e32 v35, v31, v25
	v_fmac_f32_e32 v29, 0xb102e308, v28
	v_sub_f32_e32 v28, v30, v34
	v_sub_f32_e32 v30, v31, v35
	v_rcp_f32_e32 v31, v35
	v_add_f32_e32 v36, v33, v29
	v_add_f32_e32 v25, v25, v30
	v_sub_f32_e32 v30, v36, v33
	v_sub_f32_e32 v29, v29, v30
	v_mul_f32_e32 v30, v34, v31
	v_add_f32_e32 v28, v32, v28
	v_mul_f32_e32 v32, v35, v30
	v_fma_f32 v33, v30, v35, -v32
	v_fmac_f32_e32 v33, v30, v25
	v_add_f32_e32 v37, v32, v33
	v_sub_f32_e32 v38, v34, v37
	v_sub_f32_e32 v32, v37, v32
	v_sub_f32_e32 v34, v34, v38
	v_sub_f32_e32 v32, v32, v33
	v_sub_f32_e32 v33, v34, v37
	v_add_f32_e32 v28, v28, v33
	v_add_f32_e32 v28, v32, v28
	v_add_f32_e32 v32, v38, v28
	v_mul_f32_e32 v33, v31, v32
	v_sub_f32_e32 v34, v38, v32
	v_mul_f32_e32 v37, v35, v33
	v_add_f32_e32 v28, v28, v34
	v_add_f32_e32 v34, v30, v33
	v_fma_f32 v35, v33, v35, -v37
	v_sub_f32_e32 v30, v34, v30
	v_fmac_f32_e32 v35, v33, v25
	v_sub_f32_e32 v25, v33, v30
	v_add_f32_e32 v30, v37, v35
	v_sub_f32_e32 v33, v30, v37
	v_sub_f32_e32 v37, v32, v30
	v_sub_f32_e32 v32, v32, v37
	v_sub_f32_e32 v30, v32, v30
	v_sub_f32_e32 v33, v33, v35
	v_add_f32_e32 v28, v28, v30
	v_add_f32_e32 v28, v33, v28
	v_add_f32_e32 v28, v37, v28
	v_mul_f32_e32 v28, v31, v28
	v_add_f32_e32 v25, v25, v28
	v_add_f32_e32 v28, v34, v25
	v_mul_f32_e32 v30, v28, v28
	v_fmamk_f32 v33, v30, 0x3e9b6dac, v24
	v_sub_f32_e32 v31, v28, v34
	v_ldexp_f32 v32, v28, 1
	v_mul_f32_e32 v28, v28, v30
	v_fmaak_f32 v30, v30, v33, 0x3f2aaada
	v_mul_f32_e32 v28, v28, v30
	v_add_f32_e32 v30, v32, v28
	v_sub_f32_e32 v25, v25, v31
	v_sub_f32_e32 v31, v30, v32
	v_ldexp_f32 v25, v25, 1
	v_sub_f32_e32 v28, v28, v31
	v_add_f32_e32 v25, v25, v28
	v_add_f32_e32 v28, v30, v25
	v_sub_f32_e32 v30, v28, v30
	v_add_f32_e32 v31, v36, v28
	v_sub_f32_e32 v25, v25, v30
	v_sub_f32_e32 v30, v31, v36
	v_sub_f32_e32 v32, v31, v30
	v_sub_f32_e32 v28, v28, v30
	v_add_f32_e32 v30, v29, v25
	v_sub_f32_e32 v32, v36, v32
	v_sub_f32_e32 v33, v30, v29
	v_add_f32_e32 v28, v28, v32
	v_sub_f32_e32 v32, v30, v33
	v_sub_f32_e32 v25, v25, v33
	v_sub_f32_e32 v29, v29, v32
	v_add_f32_e32 v28, v30, v28
	v_add_f32_e32 v25, v25, v29
	v_add_f32_e32 v29, v31, v28
	v_sub_f32_e32 v30, v29, v31
	v_sub_f32_e32 v28, v28, v30
	v_add_f32_e32 v25, v25, v28
	v_add_f32_e32 v25, v29, v25
	v_cmp_neq_f32_e32 vcc, s26, v0
	s_nop 1
	v_cndmask_b32_e32 v25, v23, v25, vcc
	v_cmp_lt_f32_e64 vcc, |v0|, s29
	s_nop 1
	v_cndmask_b32_e32 v0, v25, v0, vcc
	v_sub_f32_e32 v0, v12, v0
	global_store_dword v[26:27], v0, off
	global_load_dword v12, v[6:7], off offset:68
	v_add_u32_e32 v26, s12, v5
	v_ashrrev_i32_e32 v27, 31, v26
	s_waitcnt vmcnt(0)
; template <int li> __device__ __forceinline__ void layer_fwd(const Args& args, LAS unsigned char* lds, const int wid_s) {
;     ...
;                     for (int e = 0; e < 4; ++e) { const int hh = 4 * fq + e; const float f = acc[e] * rs + bfp[hh];
;                         const float lg = fminf(f, 0.f) - log1pf(expf(-fabsf(f))); logf_buf[(size_t)(bb * 16 + hh) * SEQ + s] = lg; }
	v_fmac_f32_e32 v12, v1, v11
	v_mul_f32_e64 v0, |v12|, s19
	v_fma_f32 v1, |v12|, s19, -v0
	v_rndne_f32_e32 v25, v0
	v_fma_f32 v1, |v12|, s21, v1
	v_sub_f32_e32 v0, v0, v25
	v_add_f32_e32 v0, v0, v1
	v_cvt_i32_f32_e32 v25, v25
	v_exp_f32_e32 v28, v0
	v_cmp_ngt_f32_e64 vcc, |v12|, s24
	v_min_f32_e32 v29, 0, v12
	v_lshlrev_b64 v[0:1], 14, v[26:27]
	v_ldexp_f32 v25, v28, v25
	v_cndmask_b32_e32 v25, 0, v25, vcc
	v_cmp_nlt_f32_e64 vcc, |v12|, s25
	v_lshl_add_u64 v[0:1], v[16:17], 0, v[0:1]
	s_nop 0
	v_cndmask_b32_e32 v12, v23, v25, vcc
	v_add_f32_e32 v25, 1.0, v12
	v_add_f32_e32 v28, -1.0, v25
	v_frexp_mant_f32_e32 v30, v25
	v_cvt_f64_f32_e32 v[26:27], v25
	v_sub_f32_e32 v31, v28, v25
	v_frexp_exp_i32_f64_e32 v26, v[26:27]
	v_cmp_gt_f32_e32 vcc, s27, v30
	v_sub_f32_e32 v28, v12, v28
	v_add_f32_e32 v27, 1.0, v31
	v_subbrev_co_u32_e32 v26, vcc, 0, v26, vcc
	v_add_f32_e32 v27, v28, v27
	v_sub_u32_e32 v28, 0, v26
	v_cvt_f32_i32_e32 v26, v26
	v_ldexp_f32 v25, v25, v28
	v_ldexp_f32 v27, v27, v28
	v_add_f32_e32 v28, -1.0, v25
	v_add_f32_e32 v30, 1.0, v25
	v_add_f32_e32 v31, 1.0, v28
	v_add_f32_e32 v32, -1.0, v30
	v_sub_f32_e32 v31, v25, v31
	v_sub_f32_e32 v25, v25, v32
	v_mul_f32_e32 v32, 0x3f317218, v26
	v_add_f32_e32 v31, v27, v31
	v_add_f32_e32 v25, v27, v25
	v_fma_f32 v27, v26, s28, -v32
	v_add_f32_e32 v33, v28, v31
	v_add_f32_e32 v34, v30, v25
	v_fmac_f32_e32 v27, 0xb102e308, v26
	v_sub_f32_e32 v26, v28, v33
	v_sub_f32_e32 v28, v30, v34
	v_rcp_f32_e32 v30, v34
	v_add_f32_e32 v35, v32, v27
	v_add_f32_e32 v25, v25, v28
	v_sub_f32_e32 v28, v35, v32
	v_sub_f32_e32 v27, v27, v28
	v_mul_f32_e32 v28, v33, v30
	v_add_f32_e32 v26, v31, v26
	v_mul_f32_e32 v31, v34, v28
	v_fma_f32 v32, v28, v34, -v31
	v_fmac_f32_e32 v32, v28, v25
	v_add_f32_e32 v36, v31, v32
	v_sub_f32_e32 v37, v33, v36
	v_sub_f32_e32 v31, v36, v31
	v_sub_f32_e32 v33, v33, v37
	v_sub_f32_e32 v31, v31, v32
	v_sub_f32_e32 v32, v33, v36
	v_add_f32_e32 v26, v26, v32
	v_add_f32_e32 v26, v31, v26
	v_add_f32_e32 v31, v37, v26
	v_mul_f32_e32 v32, v30, v31
	v_sub_f32_e32 v33, v37, v31
	v_mul_f32_e32 v36, v34, v32
	v_add_f32_e32 v26, v26, v33
	v_add_f32_e32 v33, v28, v32
	v_fma_f32 v34, v32, v34, -v36
	v_sub_f32_e32 v28, v33, v28
	v_fmac_f32_e32 v34, v32, v25
	v_sub_f32_e32 v25, v32, v28
	v_add_f32_e32 v28, v36, v34
	v_sub_f32_e32 v32, v28, v36
	v_sub_f32_e32 v36, v31, v28
	v_sub_f32_e32 v31, v31, v36
	v_sub_f32_e32 v28, v31, v28
	v_sub_f32_e32 v32, v32, v34
	v_add_f32_e32 v26, v26, v28
	v_add_f32_e32 v26, v32, v26
	v_add_f32_e32 v26, v36, v26
	v_mul_f32_e32 v26, v30, v26
	v_add_f32_e32 v25, v25, v26
	v_add_f32_e32 v26, v33, v25
	v_mul_f32_e32 v28, v26, v26
	v_fmamk_f32 v32, v28, 0x3e9b6dac, v24
	v_sub_f32_e32 v30, v26, v33
	v_ldexp_f32 v31, v26, 1
	v_mul_f32_e32 v26, v26, v28
	v_fmaak_f32 v28, v28, v32, 0x3f2aaada
	v_mul_f32_e32 v26, v26, v28
	v_add_f32_e32 v28, v31, v26
	v_sub_f32_e32 v25, v25, v30
	v_sub_f32_e32 v30, v28, v31
	v_ldexp_f32 v25, v25, 1
	v_sub_f32_e32 v26, v26, v30
	v_add_f32_e32 v25, v25, v26
	v_add_f32_e32 v26, v28, v25
	v_sub_f32_e32 v28, v26, v28
	v_add_f32_e32 v30, v35, v26
	v_sub_f32_e32 v25, v25, v28
	v_sub_f32_e32 v28, v30, v35
	v_sub_f32_e32 v31, v30, v28
	v_sub_f32_e32 v26, v26, v28
	v_add_f32_e32 v28, v27, v25
	v_sub_f32_e32 v31, v35, v31
	v_sub_f32_e32 v32, v28, v27
	v_add_f32_e32 v26, v26, v31
	v_sub_f32_e32 v31, v28, v32
	v_sub_f32_e32 v25, v25, v32
	v_sub_f32_e32 v27, v27, v31
	v_add_f32_e32 v26, v28, v26
	v_add_f32_e32 v25, v25, v27
	v_add_f32_e32 v27, v30, v26
	v_sub_f32_e32 v28, v27, v30
	v_sub_f32_e32 v26, v26, v28
	v_add_f32_e32 v25, v25, v26
	v_add_f32_e32 v25, v27, v25
	v_cmp_neq_f32_e32 vcc, s26, v12
	s_nop 1
	v_cndmask_b32_e32 v25, v23, v25, vcc
	v_cmp_lt_f32_e64 vcc, |v12|, s29
	s_nop 1
	v_cndmask_b32_e32 v12, v25, v12, vcc
	v_sub_f32_e32 v12, v29, v12
	global_store_dword v[0:1], v12, off
	global_load_dword v12, v[6:7], off offset:72
	v_add_u32_e32 v0, s12, v19
	v_ashrrev_i32_e32 v1, 31, v0
	v_lshlrev_b64 v[0:1], 14, v[0:1]
	v_lshl_add_u64 v[0:1], v[16:17], 0, v[0:1]
	s_waitcnt vmcnt(0)
	v_fmac_f32_e32 v12, v2, v11
	v_mul_f32_e64 v2, |v12|, s19
	v_fma_f32 v25, |v12|, s19, -v2
	v_rndne_f32_e32 v26, v2
	v_fma_f32 v25, |v12|, s21, v25
	v_sub_f32_e32 v2, v2, v26
	v_add_f32_e32 v2, v2, v25
	v_cvt_i32_f32_e32 v26, v26
	v_exp_f32_e32 v2, v2
	v_cmp_ngt_f32_e64 vcc, |v12|, s24
	v_min_f32_e32 v25, 0, v12
	v_ldexp_f32 v2, v2, v26
	v_cndmask_b32_e32 v2, 0, v2, vcc
	v_cmp_nlt_f32_e64 vcc, |v12|, s25
	s_nop 1
	v_cndmask_b32_e32 v2, v23, v2, vcc
	v_add_f32_e32 v12, 1.0, v2
	v_add_f32_e32 v28, -1.0, v12
	v_frexp_mant_f32_e32 v29, v12
	v_cvt_f64_f32_e32 v[26:27], v12
	v_sub_f32_e32 v30, v28, v12
	v_frexp_exp_i32_f64_e32 v26, v[26:27]
	v_cmp_gt_f32_e32 vcc, s27, v29
	v_sub_f32_e32 v28, v2, v28
	v_add_f32_e32 v27, 1.0, v30
	v_subbrev_co_u32_e32 v26, vcc, 0, v26, vcc
	v_add_f32_e32 v27, v28, v27
	v_sub_u32_e32 v28, 0, v26
	v_cvt_f32_i32_e32 v26, v26
	v_ldexp_f32 v12, v12, v28
	v_ldexp_f32 v27, v27, v28
	v_add_f32_e32 v28, -1.0, v12
	v_add_f32_e32 v29, 1.0, v12
	v_add_f32_e32 v30, 1.0, v28
	v_add_f32_e32 v31, -1.0, v29
	v_sub_f32_e32 v30, v12, v30
	v_sub_f32_e32 v12, v12, v31
	v_mul_f32_e32 v31, 0x3f317218, v26
	v_add_f32_e32 v30, v27, v30
	v_add_f32_e32 v12, v27, v12
	v_fma_f32 v27, v26, s28, -v31
	v_add_f32_e32 v32, v28, v30
	v_add_f32_e32 v33, v29, v12
	v_fmac_f32_e32 v27, 0xb102e308, v26
	v_sub_f32_e32 v26, v28, v32
	v_sub_f32_e32 v28, v29, v33
	v_rcp_f32_e32 v29, v33
	v_add_f32_e32 v34, v31, v27
	v_add_f32_e32 v12, v12, v28
	v_sub_f32_e32 v28, v34, v31
	v_sub_f32_e32 v27, v27, v28
	v_mul_f32_e32 v28, v32, v29
	v_add_f32_e32 v26, v30, v26
	v_mul_f32_e32 v30, v33, v28
; template <int li> __device__ __forceinline__ void layer_fwd(const Args& args, LAS unsigned char* lds, const int wid_s) {
;     ...
;                 for (int task = gw; task < M / 16; task += NGW) {
;     ...
;                     for (int e = 0; e < 4; ++e) { const int hh = 4 * fq + e; const float f = acc[e] * rs + bfp[hh];
;                         const float lg = fminf(f, 0.f) - log1pf(expf(-fabsf(f))); logf_buf[(size_t)(bb * 16 + hh) * SEQ + s] = lg; }
	v_fma_f32 v31, v28, v33, -v30
	v_fmac_f32_e32 v31, v28, v12
	v_add_f32_e32 v35, v30, v31
	v_sub_f32_e32 v36, v32, v35
	v_sub_f32_e32 v30, v35, v30
	v_sub_f32_e32 v32, v32, v36
	v_sub_f32_e32 v30, v30, v31
	v_sub_f32_e32 v31, v32, v35
	v_add_f32_e32 v26, v26, v31
	v_add_f32_e32 v26, v30, v26
	v_add_f32_e32 v30, v36, v26
	v_mul_f32_e32 v31, v29, v30
	v_sub_f32_e32 v32, v36, v30
	v_mul_f32_e32 v35, v33, v31
	v_add_f32_e32 v26, v26, v32
	v_add_f32_e32 v32, v28, v31
	v_fma_f32 v33, v31, v33, -v35
	v_sub_f32_e32 v28, v32, v28
	v_fmac_f32_e32 v33, v31, v12
	v_sub_f32_e32 v12, v31, v28
	v_add_f32_e32 v28, v35, v33
	v_sub_f32_e32 v31, v28, v35
	v_sub_f32_e32 v35, v30, v28
	v_sub_f32_e32 v30, v30, v35
	v_sub_f32_e32 v28, v30, v28
	v_sub_f32_e32 v31, v31, v33
	v_add_f32_e32 v26, v26, v28
	v_add_f32_e32 v26, v31, v26
	v_add_f32_e32 v26, v35, v26
	v_mul_f32_e32 v26, v29, v26
	v_add_f32_e32 v12, v12, v26
	v_add_f32_e32 v26, v32, v12
	v_mul_f32_e32 v28, v26, v26
	v_fmamk_f32 v31, v28, 0x3e9b6dac, v24
	v_sub_f32_e32 v29, v26, v32
	v_ldexp_f32 v30, v26, 1
	v_mul_f32_e32 v26, v26, v28
	v_fmaak_f32 v28, v28, v31, 0x3f2aaada
	v_mul_f32_e32 v26, v26, v28
	v_add_f32_e32 v28, v30, v26
	v_sub_f32_e32 v12, v12, v29
	v_sub_f32_e32 v29, v28, v30
	v_ldexp_f32 v12, v12, 1
	v_sub_f32_e32 v26, v26, v29
	v_add_f32_e32 v12, v12, v26
	v_add_f32_e32 v26, v28, v12
	v_sub_f32_e32 v28, v26, v28
	v_add_f32_e32 v29, v34, v26
	v_sub_f32_e32 v12, v12, v28
	v_sub_f32_e32 v28, v29, v34
	v_sub_f32_e32 v30, v29, v28
	v_sub_f32_e32 v26, v26, v28
	v_add_f32_e32 v28, v27, v12
	v_sub_f32_e32 v30, v34, v30
	v_sub_f32_e32 v31, v28, v27
	v_add_f32_e32 v26, v26, v30
	v_sub_f32_e32 v30, v28, v31
	v_sub_f32_e32 v12, v12, v31
	v_sub_f32_e32 v27, v27, v30
	v_add_f32_e32 v26, v28, v26
	v_add_f32_e32 v12, v12, v27
	v_add_f32_e32 v27, v29, v26
	v_sub_f32_e32 v28, v27, v29
	v_sub_f32_e32 v26, v26, v28
	v_add_f32_e32 v12, v12, v26
	v_add_f32_e32 v12, v27, v12
	v_cmp_neq_f32_e32 vcc, s26, v2
	s_nop 1
	v_cndmask_b32_e32 v12, v23, v12, vcc
	v_cmp_lt_f32_e64 vcc, |v2|, s29
	s_nop 1
	v_cndmask_b32_e32 v2, v12, v2, vcc
	v_sub_f32_e32 v2, v25, v2
	global_store_dword v[0:1], v2, off
	global_load_dword v2, v[6:7], off offset:76
	v_add_u32_e32 v0, s12, v20
	v_ashrrev_i32_e32 v1, 31, v0
	v_lshlrev_b64 v[0:1], 14, v[0:1]
	v_lshl_add_u64 v[0:1], v[16:17], 0, v[0:1]
	s_waitcnt vmcnt(0)
	v_fmac_f32_e32 v2, v3, v11
	v_mul_f32_e64 v3, |v2|, s19
	v_fma_f32 v11, |v2|, s19, -v3
	v_rndne_f32_e32 v12, v3
	v_fma_f32 v11, |v2|, s21, v11
	v_sub_f32_e32 v3, v3, v12
	v_add_f32_e32 v3, v3, v11
	v_cvt_i32_f32_e32 v12, v12
	v_exp_f32_e32 v3, v3
	v_cmp_ngt_f32_e64 vcc, |v2|, s24
	v_min_f32_e32 v11, 0, v2
	v_ldexp_f32 v3, v3, v12
	v_cndmask_b32_e32 v3, 0, v3, vcc
	v_cmp_nlt_f32_e64 vcc, |v2|, s25
	s_nop 1
	v_cndmask_b32_e32 v12, v23, v3, vcc
	v_add_f32_e32 v16, 1.0, v12
	v_add_f32_e32 v17, -1.0, v16
	v_frexp_mant_f32_e32 v25, v16
	v_cvt_f64_f32_e32 v[2:3], v16
	v_sub_f32_e32 v26, v17, v16
	v_frexp_exp_i32_f64_e32 v2, v[2:3]
	v_cmp_gt_f32_e32 vcc, s27, v25
	v_sub_f32_e32 v17, v12, v17
	v_add_f32_e32 v3, 1.0, v26
	v_subbrev_co_u32_e32 v2, vcc, 0, v2, vcc
	v_add_f32_e32 v3, v17, v3
	v_sub_u32_e32 v17, 0, v2
	v_cvt_f32_i32_e32 v2, v2
	v_ldexp_f32 v16, v16, v17
	v_ldexp_f32 v3, v3, v17
	v_add_f32_e32 v17, -1.0, v16
	v_add_f32_e32 v25, 1.0, v16
	v_add_f32_e32 v26, 1.0, v17
	v_add_f32_e32 v27, -1.0, v25
	v_sub_f32_e32 v26, v16, v26
	v_sub_f32_e32 v16, v16, v27
	v_mul_f32_e32 v27, 0x3f317218, v2
	v_add_f32_e32 v26, v3, v26
	v_add_f32_e32 v3, v3, v16
	v_fma_f32 v16, v2, s28, -v27
	v_add_f32_e32 v28, v17, v26
	v_add_f32_e32 v29, v25, v3
	v_fmac_f32_e32 v16, 0xb102e308, v2
	v_sub_f32_e32 v2, v17, v28
	v_sub_f32_e32 v17, v25, v29
	v_rcp_f32_e32 v25, v29
	v_add_f32_e32 v30, v27, v16
	v_add_f32_e32 v3, v3, v17
	v_sub_f32_e32 v17, v30, v27
	v_sub_f32_e32 v16, v16, v17
	v_mul_f32_e32 v17, v28, v25
	v_add_f32_e32 v2, v26, v2
	v_mul_f32_e32 v26, v29, v17
	v_fma_f32 v27, v17, v29, -v26
	v_fmac_f32_e32 v27, v17, v3
	v_add_f32_e32 v31, v26, v27
	v_sub_f32_e32 v32, v28, v31
	v_sub_f32_e32 v26, v31, v26
	v_sub_f32_e32 v28, v28, v32
	v_sub_f32_e32 v26, v26, v27
	v_sub_f32_e32 v27, v28, v31
	v_add_f32_e32 v2, v2, v27
	v_add_f32_e32 v2, v26, v2
	v_add_f32_e32 v26, v32, v2
	v_mul_f32_e32 v27, v25, v26
	v_sub_f32_e32 v28, v32, v26
	v_mul_f32_e32 v31, v29, v27
	v_add_f32_e32 v2, v2, v28
	v_add_f32_e32 v28, v17, v27
	v_fma_f32 v29, v27, v29, -v31
	v_sub_f32_e32 v17, v28, v17
	v_fmac_f32_e32 v29, v27, v3
	v_sub_f32_e32 v3, v27, v17
	v_add_f32_e32 v17, v31, v29
	v_sub_f32_e32 v27, v17, v31
	v_sub_f32_e32 v31, v26, v17
	v_sub_f32_e32 v26, v26, v31
	v_sub_f32_e32 v17, v26, v17
	v_sub_f32_e32 v27, v27, v29
	v_add_f32_e32 v2, v2, v17
	v_add_f32_e32 v2, v27, v2
	v_add_f32_e32 v2, v31, v2
	v_mul_f32_e32 v2, v25, v2
	v_add_f32_e32 v2, v3, v2
	v_add_f32_e32 v3, v28, v2
	v_mul_f32_e32 v17, v3, v3
	v_fmamk_f32 v27, v17, 0x3e9b6dac, v24
	v_sub_f32_e32 v25, v3, v28
	v_ldexp_f32 v26, v3, 1
	v_mul_f32_e32 v3, v3, v17
	v_fmaak_f32 v17, v17, v27, 0x3f2aaada
	v_mul_f32_e32 v3, v3, v17
	v_add_f32_e32 v17, v26, v3
	v_sub_f32_e32 v2, v2, v25
	v_sub_f32_e32 v25, v17, v26
	v_ldexp_f32 v2, v2, 1
	v_sub_f32_e32 v3, v3, v25
	v_add_f32_e32 v2, v2, v3
	v_add_f32_e32 v3, v17, v2
	v_sub_f32_e32 v17, v3, v17
	v_add_f32_e32 v25, v30, v3
	v_sub_f32_e32 v2, v2, v17
	v_sub_f32_e32 v17, v25, v30
	v_sub_f32_e32 v26, v25, v17
	v_sub_f32_e32 v3, v3, v17
	v_add_f32_e32 v17, v16, v2
	v_sub_f32_e32 v26, v30, v26
	v_sub_f32_e32 v27, v17, v16
	v_add_f32_e32 v3, v3, v26
	v_sub_f32_e32 v26, v17, v27
	v_sub_f32_e32 v2, v2, v27
	v_sub_f32_e32 v16, v16, v26
	v_add_f32_e32 v3, v17, v3
	v_add_f32_e32 v2, v2, v16
	v_add_f32_e32 v16, v25, v3
	v_sub_f32_e32 v17, v16, v25
	v_sub_f32_e32 v3, v3, v17
	v_add_f32_e32 v2, v2, v3
	v_add_f32_e32 v2, v16, v2
	v_cmp_neq_f32_e32 vcc, s26, v12
	s_nop 1
	v_cndmask_b32_e32 v2, v23, v2, vcc
	v_cmp_lt_f32_e64 vcc, |v12|, s29
	s_nop 1
	v_cndmask_b32_e32 v2, v2, v12, vcc
	v_sub_f32_e32 v2, v11, v2
	global_store_dword v[0:1], v2, off
	s_cbranch_scc0 .LBB0_1630
